# stack j + the per-XCD release atomic nobody polls any more removed from the 12 loop barrier sites
# baseline (speedup 1.0000x reference)
; __device__ __forceinline__ unsigned xb_ld(unsigned* p)              { return __hip_atomic_load(p, __ATOMIC_RELAXED, __HIP_MEMORY_SCOPE_AGENT); }
; __device__ __forceinline__ unsigned xb_add(unsigned* p, unsigned v) { return __hip_atomic_fetch_add(p, v, __ATOMIC_RELAXED, __HIP_MEMORY_SCOPE_AGENT); }
; #define XB_SPIN(cond, bar) do { unsigned _sp = 0; while (cond) { __builtin_amdgcn_s_sleep(1); \
;     if ((++_sp & 255u) == 0u) { if (xb_ld(&(bar)[XB_TMO])) break; if (_sp > XB_SPIN_CAP) { atomicAdd(&(bar)[XB_TMO], 1u); break; } } } } while (0)
; __device__ __forceinline__ void xcd_barrier(const XcdBarrier& b) {
;     ...
;         if (old + 1u == (gen + 1u) * nloc) {
;             __builtin_amdgcn_fence(__ATOMIC_RELEASE, "agent");
;             asm volatile("s_waitcnt vmcnt(0)" ::: "memory");
;             const unsigned og = xb_add(&bar[XB_TOP], 1u);
;             const unsigned tg = og / nx;
;             if (og + 1u == (tg + 1u) * nx) xb_add(&bar[XB_TOPGEN], 1u);
;             else XB_SPIN(xb_ld(&bar[XB_TOPGEN]) == tg, bar);
;             __builtin_amdgcn_fence(__ATOMIC_ACQUIRE, "agent");
;             xb_add(&bar[XB_XGEN(b.x)], 1u);
;             asm volatile("s_waitcnt vmcnt(0)" ::: "memory");
.LBB0_2203:
	s_or_b64 exec, exec, s[10:11]
	s_mov_b64 s[10:11], exec
	v_mbcnt_lo_u32_b32 v0, s10, 0
	v_mbcnt_hi_u32_b32 v0, s11, v0
	v_cmp_eq_u32_e32 vcc, 0, v0
	s_waitcnt vmcnt(0)
	buffer_inv sc1
	s_and_saveexec_b64 s[38:39], vcc
	s_cbranch_execz .LBB0_2205
	s_bcnt1_i32_b64 s6, s[10:11]
	v_mov_b32_e32 v0, s6
	v_readlane_b32 s6, v252, 53
	v_readlane_b32 s7, v252, 54
	s_nop 4
.LBB0_2205:
	s_or_b64 exec, exec, s[38:39]
	s_waitcnt vmcnt(0)

; __device__ __forceinline__ unsigned xb_ld(unsigned* p)              { return __hip_atomic_load(p, __ATOMIC_RELAXED, __HIP_MEMORY_SCOPE_AGENT); }
; __device__ __forceinline__ unsigned xb_add(unsigned* p, unsigned v) { return __hip_atomic_fetch_add(p, v, __ATOMIC_RELAXED, __HIP_MEMORY_SCOPE_AGENT); }
; #define XB_SPIN(cond, bar) do { unsigned _sp = 0; while (cond) { __builtin_amdgcn_s_sleep(1); \
;     if ((++_sp & 255u) == 0u) { if (xb_ld(&(bar)[XB_TMO])) break; if (_sp > XB_SPIN_CAP) { atomicAdd(&(bar)[XB_TMO], 1u); break; } } } } while (0)
; __device__ __forceinline__ void xcd_barrier(const XcdBarrier& b) {
;     ...
;         if (old + 1u == (gen + 1u) * nloc) {
;             __builtin_amdgcn_fence(__ATOMIC_RELEASE, "agent");
;             asm volatile("s_waitcnt vmcnt(0)" ::: "memory");
;             const unsigned og = xb_add(&bar[XB_TOP], 1u);
;             const unsigned tg = og / nx;
;             if (og + 1u == (tg + 1u) * nx) xb_add(&bar[XB_TOPGEN], 1u);
;             else XB_SPIN(xb_ld(&bar[XB_TOPGEN]) == tg, bar);
;             __builtin_amdgcn_fence(__ATOMIC_ACQUIRE, "agent");
;             xb_add(&bar[XB_XGEN(b.x)], 1u);
;             asm volatile("s_waitcnt vmcnt(0)" ::: "memory");
.LBB0_2553:
	s_or_b64 exec, exec, s[2:3]
	s_mov_b64 s[2:3], exec
	v_mbcnt_lo_u32_b32 v0, s2, 0
	v_mbcnt_hi_u32_b32 v0, s3, v0
	v_cmp_eq_u32_e32 vcc, 0, v0
	s_waitcnt vmcnt(0)
	buffer_inv sc1
	s_and_saveexec_b64 s[38:39], vcc
	s_cbranch_execz .LBB0_2555
	s_bcnt1_i32_b64 s2, s[2:3]
	v_mov_b32_e32 v0, s2
	v_readlane_b32 s2, v252, 53
	v_readlane_b32 s3, v252, 54
	s_nop 4
.LBB0_2555:
	s_or_b64 exec, exec, s[38:39]
	s_waitcnt vmcnt(0)

; __device__ __forceinline__ unsigned xb_ld(unsigned* p)              { return __hip_atomic_load(p, __ATOMIC_RELAXED, __HIP_MEMORY_SCOPE_AGENT); }
; __device__ __forceinline__ unsigned xb_add(unsigned* p, unsigned v) { return __hip_atomic_fetch_add(p, v, __ATOMIC_RELAXED, __HIP_MEMORY_SCOPE_AGENT); }
; #define XB_SPIN(cond, bar) do { unsigned _sp = 0; while (cond) { __builtin_amdgcn_s_sleep(1); \
;     if ((++_sp & 255u) == 0u) { if (xb_ld(&(bar)[XB_TMO])) break; if (_sp > XB_SPIN_CAP) { atomicAdd(&(bar)[XB_TMO], 1u); break; } } } } while (0)
; __device__ __forceinline__ void xcd_barrier(const XcdBarrier& b) {
;     ...
;         if (old + 1u == (gen + 1u) * nloc) {
;             __builtin_amdgcn_fence(__ATOMIC_RELEASE, "agent");
;             asm volatile("s_waitcnt vmcnt(0)" ::: "memory");
;             const unsigned og = xb_add(&bar[XB_TOP], 1u);
;             const unsigned tg = og / nx;
;             if (og + 1u == (tg + 1u) * nx) xb_add(&bar[XB_TOPGEN], 1u);
;             else XB_SPIN(xb_ld(&bar[XB_TOPGEN]) == tg, bar);
;             __builtin_amdgcn_fence(__ATOMIC_ACQUIRE, "agent");
;             xb_add(&bar[XB_XGEN(b.x)], 1u);
;             asm volatile("s_waitcnt vmcnt(0)" ::: "memory");
.LBB0_2647:
	s_or_b64 exec, exec, s[2:3]
	s_mov_b64 s[2:3], exec
	v_mbcnt_lo_u32_b32 v0, s2, 0
	v_mbcnt_hi_u32_b32 v0, s3, v0
	v_cmp_eq_u32_e32 vcc, 0, v0
	s_waitcnt vmcnt(0)
	buffer_inv sc1
	s_and_saveexec_b64 s[38:39], vcc
	s_cbranch_execz .LBB0_2649
	s_bcnt1_i32_b64 s2, s[2:3]
	v_mov_b32_e32 v0, s2
	v_readlane_b32 s2, v252, 53
	v_readlane_b32 s3, v252, 54
	s_nop 4
.LBB0_2649:
	s_or_b64 exec, exec, s[38:39]
	s_waitcnt vmcnt(0)

; __device__ __forceinline__ unsigned xb_ld(unsigned* p)              { return __hip_atomic_load(p, __ATOMIC_RELAXED, __HIP_MEMORY_SCOPE_AGENT); }
; __device__ __forceinline__ unsigned xb_add(unsigned* p, unsigned v) { return __hip_atomic_fetch_add(p, v, __ATOMIC_RELAXED, __HIP_MEMORY_SCOPE_AGENT); }
; #define XB_SPIN(cond, bar) do { unsigned _sp = 0; while (cond) { __builtin_amdgcn_s_sleep(1); \
;     if ((++_sp & 255u) == 0u) { if (xb_ld(&(bar)[XB_TMO])) break; if (_sp > XB_SPIN_CAP) { atomicAdd(&(bar)[XB_TMO], 1u); break; } } } } while (0)
; __device__ __forceinline__ void xcd_barrier(const XcdBarrier& b) {
;     ...
;         if (old + 1u == (gen + 1u) * nloc) {
;             __builtin_amdgcn_fence(__ATOMIC_RELEASE, "agent");
;             asm volatile("s_waitcnt vmcnt(0)" ::: "memory");
;             const unsigned og = xb_add(&bar[XB_TOP], 1u);
;             const unsigned tg = og / nx;
;             if (og + 1u == (tg + 1u) * nx) xb_add(&bar[XB_TOPGEN], 1u);
;             else XB_SPIN(xb_ld(&bar[XB_TOPGEN]) == tg, bar);
;             __builtin_amdgcn_fence(__ATOMIC_ACQUIRE, "agent");
;             xb_add(&bar[XB_XGEN(b.x)], 1u);
;             asm volatile("s_waitcnt vmcnt(0)" ::: "memory");
.LBB0_2708:
	s_or_b64 exec, exec, s[10:11]
	s_mov_b64 s[10:11], exec
	v_mbcnt_lo_u32_b32 v0, s10, 0
	v_mbcnt_hi_u32_b32 v0, s11, v0
	v_cmp_eq_u32_e32 vcc, 0, v0
	s_waitcnt vmcnt(0)
	buffer_inv sc1
	s_and_saveexec_b64 s[38:39], vcc
	s_cbranch_execz .LBB0_2710
	s_bcnt1_i32_b64 s6, s[10:11]
	v_mov_b32_e32 v0, s6
	v_readlane_b32 s6, v252, 53
	v_readlane_b32 s7, v252, 54
	s_nop 4
.LBB0_2710:
	s_or_b64 exec, exec, s[38:39]
	s_waitcnt vmcnt(0)

; __device__ __forceinline__ unsigned xb_ld(unsigned* p)              { return __hip_atomic_load(p, __ATOMIC_RELAXED, __HIP_MEMORY_SCOPE_AGENT); }
; __device__ __forceinline__ unsigned xb_add(unsigned* p, unsigned v) { return __hip_atomic_fetch_add(p, v, __ATOMIC_RELAXED, __HIP_MEMORY_SCOPE_AGENT); }
; #define XB_SPIN(cond, bar) do { unsigned _sp = 0; while (cond) { __builtin_amdgcn_s_sleep(1); \
;     if ((++_sp & 255u) == 0u) { if (xb_ld(&(bar)[XB_TMO])) break; if (_sp > XB_SPIN_CAP) { atomicAdd(&(bar)[XB_TMO], 1u); break; } } } } while (0)
; __device__ __forceinline__ void xcd_barrier(const XcdBarrier& b) {
;     ...
;         if (old + 1u == (gen + 1u) * nloc) {
;             __builtin_amdgcn_fence(__ATOMIC_RELEASE, "agent");
;             asm volatile("s_waitcnt vmcnt(0)" ::: "memory");
;             const unsigned og = xb_add(&bar[XB_TOP], 1u);
;             const unsigned tg = og / nx;
;             if (og + 1u == (tg + 1u) * nx) xb_add(&bar[XB_TOPGEN], 1u);
;             else XB_SPIN(xb_ld(&bar[XB_TOPGEN]) == tg, bar);
;             __builtin_amdgcn_fence(__ATOMIC_ACQUIRE, "agent");
;             xb_add(&bar[XB_XGEN(b.x)], 1u);
;             asm volatile("s_waitcnt vmcnt(0)" ::: "memory");
.LBB0_3070:
	s_or_b64 exec, exec, s[10:11]
	s_mov_b64 s[10:11], exec
	v_mbcnt_lo_u32_b32 v0, s10, 0
	v_mbcnt_hi_u32_b32 v0, s11, v0
	v_cmp_eq_u32_e32 vcc, 0, v0
	s_waitcnt vmcnt(0)
	buffer_inv sc1
	s_and_saveexec_b64 s[38:39], vcc
	s_cbranch_execz .LBB0_3072
	s_bcnt1_i32_b64 s6, s[10:11]
	v_mov_b32_e32 v0, s6
	v_readlane_b32 s6, v252, 53
	v_readlane_b32 s7, v252, 54
	s_nop 4
.LBB0_3072:
	s_or_b64 exec, exec, s[38:39]
	s_waitcnt vmcnt(0)

; __device__ __forceinline__ unsigned xb_ld(unsigned* p)              { return __hip_atomic_load(p, __ATOMIC_RELAXED, __HIP_MEMORY_SCOPE_AGENT); }
; __device__ __forceinline__ unsigned xb_add(unsigned* p, unsigned v) { return __hip_atomic_fetch_add(p, v, __ATOMIC_RELAXED, __HIP_MEMORY_SCOPE_AGENT); }
; #define XB_SPIN(cond, bar) do { unsigned _sp = 0; while (cond) { __builtin_amdgcn_s_sleep(1); \
;     if ((++_sp & 255u) == 0u) { if (xb_ld(&(bar)[XB_TMO])) break; if (_sp > XB_SPIN_CAP) { atomicAdd(&(bar)[XB_TMO], 1u); break; } } } } while (0)
; __device__ __forceinline__ void xcd_barrier(const XcdBarrier& b) {
;     ...
;         if (old + 1u == (gen + 1u) * nloc) {
;             __builtin_amdgcn_fence(__ATOMIC_RELEASE, "agent");
;             asm volatile("s_waitcnt vmcnt(0)" ::: "memory");
;             const unsigned og = xb_add(&bar[XB_TOP], 1u);
;             const unsigned tg = og / nx;
;             if (og + 1u == (tg + 1u) * nx) xb_add(&bar[XB_TOPGEN], 1u);
;             else XB_SPIN(xb_ld(&bar[XB_TOPGEN]) == tg, bar);
;             __builtin_amdgcn_fence(__ATOMIC_ACQUIRE, "agent");
;             xb_add(&bar[XB_XGEN(b.x)], 1u);
;             asm volatile("s_waitcnt vmcnt(0)" ::: "memory");
.LBB0_3259:
	s_or_b64 exec, exec, s[38:39]
	s_mov_b64 s[38:39], exec
	v_mbcnt_lo_u32_b32 v0, s38, 0
	v_mbcnt_hi_u32_b32 v0, s39, v0
	v_cmp_eq_u32_e32 vcc, 0, v0
	s_waitcnt vmcnt(0)
	buffer_inv sc1
	s_and_saveexec_b64 s[40:41], vcc
	s_cbranch_execz .LBB0_3261
	s_bcnt1_i32_b64 s6, s[38:39]
	v_mov_b32_e32 v0, s6
	v_readlane_b32 s6, v252, 53
	v_readlane_b32 s7, v252, 54
	s_nop 4
.LBB0_3261:
	s_or_b64 exec, exec, s[40:41]
	s_waitcnt vmcnt(0)

; __device__ __forceinline__ unsigned xb_ld(unsigned* p)              { return __hip_atomic_load(p, __ATOMIC_RELAXED, __HIP_MEMORY_SCOPE_AGENT); }
; __device__ __forceinline__ unsigned xb_add(unsigned* p, unsigned v) { return __hip_atomic_fetch_add(p, v, __ATOMIC_RELAXED, __HIP_MEMORY_SCOPE_AGENT); }
; #define XB_SPIN(cond, bar) do { unsigned _sp = 0; while (cond) { __builtin_amdgcn_s_sleep(1); \
;     if ((++_sp & 255u) == 0u) { if (xb_ld(&(bar)[XB_TMO])) break; if (_sp > XB_SPIN_CAP) { atomicAdd(&(bar)[XB_TMO], 1u); break; } } } } while (0)
; __device__ __forceinline__ void xcd_barrier(const XcdBarrier& b) {
;     ...
;         if (old + 1u == (gen + 1u) * nloc) {
;             __builtin_amdgcn_fence(__ATOMIC_RELEASE, "agent");
;             asm volatile("s_waitcnt vmcnt(0)" ::: "memory");
;             const unsigned og = xb_add(&bar[XB_TOP], 1u);
;             const unsigned tg = og / nx;
;             if (og + 1u == (tg + 1u) * nx) xb_add(&bar[XB_TOPGEN], 1u);
;             else XB_SPIN(xb_ld(&bar[XB_TOPGEN]) == tg, bar);
;             __builtin_amdgcn_fence(__ATOMIC_ACQUIRE, "agent");
;             xb_add(&bar[XB_XGEN(b.x)], 1u);
;             asm volatile("s_waitcnt vmcnt(0)" ::: "memory");
.LBB0_3382:
	s_or_b64 exec, exec, s[38:39]
	s_mov_b64 s[38:39], exec
	v_mbcnt_lo_u32_b32 v0, s38, 0
	v_mbcnt_hi_u32_b32 v0, s39, v0
	v_cmp_eq_u32_e32 vcc, 0, v0
	s_waitcnt vmcnt(0)
	buffer_inv sc1
	s_and_saveexec_b64 s[40:41], vcc
	s_cbranch_execz .LBB0_3384
	s_bcnt1_i32_b64 s6, s[38:39]
	v_mov_b32_e32 v0, s6
	v_readlane_b32 s6, v252, 53
	v_readlane_b32 s7, v252, 54
	s_nop 4
.LBB0_3384:
	s_or_b64 exec, exec, s[40:41]
	s_waitcnt vmcnt(0)

; __device__ __forceinline__ unsigned xb_ld(unsigned* p)              { return __hip_atomic_load(p, __ATOMIC_RELAXED, __HIP_MEMORY_SCOPE_AGENT); }
; __device__ __forceinline__ unsigned xb_add(unsigned* p, unsigned v) { return __hip_atomic_fetch_add(p, v, __ATOMIC_RELAXED, __HIP_MEMORY_SCOPE_AGENT); }
; #define XB_SPIN(cond, bar) do { unsigned _sp = 0; while (cond) { __builtin_amdgcn_s_sleep(1); \
;     if ((++_sp & 255u) == 0u) { if (xb_ld(&(bar)[XB_TMO])) break; if (_sp > XB_SPIN_CAP) { atomicAdd(&(bar)[XB_TMO], 1u); break; } } } } while (0)
; __device__ __forceinline__ void xcd_barrier(const XcdBarrier& b) {
;     ...
;         if (old + 1u == (gen + 1u) * nloc) {
;             __builtin_amdgcn_fence(__ATOMIC_RELEASE, "agent");
;             asm volatile("s_waitcnt vmcnt(0)" ::: "memory");
;             const unsigned og = xb_add(&bar[XB_TOP], 1u);
;             const unsigned tg = og / nx;
;             if (og + 1u == (tg + 1u) * nx) xb_add(&bar[XB_TOPGEN], 1u);
;             else XB_SPIN(xb_ld(&bar[XB_TOPGEN]) == tg, bar);
;             __builtin_amdgcn_fence(__ATOMIC_ACQUIRE, "agent");
;             xb_add(&bar[XB_XGEN(b.x)], 1u);
;             asm volatile("s_waitcnt vmcnt(0)" ::: "memory");
.LBB0_3548:
	s_or_b64 exec, exec, s[38:39]
	s_mov_b64 s[38:39], exec
	v_mbcnt_lo_u32_b32 v0, s38, 0
	v_mbcnt_hi_u32_b32 v0, s39, v0
	v_cmp_eq_u32_e32 vcc, 0, v0
	s_waitcnt vmcnt(0)
	buffer_inv sc1
	s_and_saveexec_b64 s[40:41], vcc
	s_cbranch_execz .LBB0_3550
	s_bcnt1_i32_b64 s6, s[38:39]
	v_mov_b32_e32 v0, s6
	v_readlane_b32 s6, v252, 53
	v_readlane_b32 s7, v252, 54
	s_nop 4
.LBB0_3550:
	s_or_b64 exec, exec, s[40:41]
	s_waitcnt vmcnt(0)

; __device__ __forceinline__ unsigned xb_ld(unsigned* p)              { return __hip_atomic_load(p, __ATOMIC_RELAXED, __HIP_MEMORY_SCOPE_AGENT); }
; __device__ __forceinline__ unsigned xb_add(unsigned* p, unsigned v) { return __hip_atomic_fetch_add(p, v, __ATOMIC_RELAXED, __HIP_MEMORY_SCOPE_AGENT); }
; #define XB_SPIN(cond, bar) do { unsigned _sp = 0; while (cond) { __builtin_amdgcn_s_sleep(1); \
;     if ((++_sp & 255u) == 0u) { if (xb_ld(&(bar)[XB_TMO])) break; if (_sp > XB_SPIN_CAP) { atomicAdd(&(bar)[XB_TMO], 1u); break; } } } } while (0)
; __device__ __forceinline__ void xcd_barrier(const XcdBarrier& b) {
;     ...
;         if (old + 1u == (gen + 1u) * nloc) {
;             __builtin_amdgcn_fence(__ATOMIC_RELEASE, "agent");
;             asm volatile("s_waitcnt vmcnt(0)" ::: "memory");
;             const unsigned og = xb_add(&bar[XB_TOP], 1u);
;             const unsigned tg = og / nx;
;             if (og + 1u == (tg + 1u) * nx) xb_add(&bar[XB_TOPGEN], 1u);
;             else XB_SPIN(xb_ld(&bar[XB_TOPGEN]) == tg, bar);
;             __builtin_amdgcn_fence(__ATOMIC_ACQUIRE, "agent");
;             xb_add(&bar[XB_XGEN(b.x)], 1u);
;             asm volatile("s_waitcnt vmcnt(0)" ::: "memory");
.LBB0_3642:
	s_or_b64 exec, exec, s[38:39]
	s_mov_b64 s[38:39], exec
	v_mbcnt_lo_u32_b32 v0, s38, 0
	v_mbcnt_hi_u32_b32 v0, s39, v0
	v_cmp_eq_u32_e32 vcc, 0, v0
	s_waitcnt vmcnt(0)
	buffer_inv sc1
	s_and_saveexec_b64 s[40:41], vcc
	s_cbranch_execz .LBB0_3644
	s_bcnt1_i32_b64 s4, s[38:39]
	v_readlane_b32 s22, v252, 53
	v_mov_b32_e32 v0, s4
	v_readlane_b32 s23, v252, 54
	s_nop 4
.LBB0_3644:
	s_or_b64 exec, exec, s[40:41]
	s_waitcnt vmcnt(0)

; __device__ __forceinline__ unsigned xb_ld(unsigned* p)              { return __hip_atomic_load(p, __ATOMIC_RELAXED, __HIP_MEMORY_SCOPE_AGENT); }
; __device__ __forceinline__ unsigned xb_add(unsigned* p, unsigned v) { return __hip_atomic_fetch_add(p, v, __ATOMIC_RELAXED, __HIP_MEMORY_SCOPE_AGENT); }
; #define XB_SPIN(cond, bar) do { unsigned _sp = 0; while (cond) { __builtin_amdgcn_s_sleep(1); \
;     if ((++_sp & 255u) == 0u) { if (xb_ld(&(bar)[XB_TMO])) break; if (_sp > XB_SPIN_CAP) { atomicAdd(&(bar)[XB_TMO], 1u); break; } } } } while (0)
; __device__ __forceinline__ void xcd_barrier(const XcdBarrier& b) {
;     ...
;         if (old + 1u == (gen + 1u) * nloc) {
;             __builtin_amdgcn_fence(__ATOMIC_RELEASE, "agent");
;             asm volatile("s_waitcnt vmcnt(0)" ::: "memory");
;             const unsigned og = xb_add(&bar[XB_TOP], 1u);
;             const unsigned tg = og / nx;
;             if (og + 1u == (tg + 1u) * nx) xb_add(&bar[XB_TOPGEN], 1u);
;             else XB_SPIN(xb_ld(&bar[XB_TOPGEN]) == tg, bar);
;             __builtin_amdgcn_fence(__ATOMIC_ACQUIRE, "agent");
;             xb_add(&bar[XB_XGEN(b.x)], 1u);
;             asm volatile("s_waitcnt vmcnt(0)" ::: "memory");
.LBB0_3703:
	s_or_b64 exec, exec, s[38:39]
	s_mov_b64 s[38:39], exec
	v_mbcnt_lo_u32_b32 v0, s38, 0
	v_mbcnt_hi_u32_b32 v0, s39, v0
	v_cmp_eq_u32_e32 vcc, 0, v0
	s_waitcnt vmcnt(0)
	buffer_inv sc1
	s_and_saveexec_b64 s[40:41], vcc
	s_cbranch_execz .LBB0_3705
	s_bcnt1_i32_b64 s7, s[38:39]
	v_readlane_b32 s22, v252, 53
	v_mov_b32_e32 v0, s7
	v_readlane_b32 s23, v252, 54
	s_nop 4
.LBB0_3705:
	s_or_b64 exec, exec, s[40:41]
	s_waitcnt vmcnt(0)

; __device__ __forceinline__ unsigned xb_ld(unsigned* p)              { return __hip_atomic_load(p, __ATOMIC_RELAXED, __HIP_MEMORY_SCOPE_AGENT); }
; __device__ __forceinline__ unsigned xb_add(unsigned* p, unsigned v) { return __hip_atomic_fetch_add(p, v, __ATOMIC_RELAXED, __HIP_MEMORY_SCOPE_AGENT); }
; #define XB_SPIN(cond, bar) do { unsigned _sp = 0; while (cond) { __builtin_amdgcn_s_sleep(1); \
;     if ((++_sp & 255u) == 0u) { if (xb_ld(&(bar)[XB_TMO])) break; if (_sp > XB_SPIN_CAP) { atomicAdd(&(bar)[XB_TMO], 1u); break; } } } } while (0)
; __device__ __forceinline__ void xcd_barrier(const XcdBarrier& b) {
;     ...
;         if (old + 1u == (gen + 1u) * nloc) {
;             __builtin_amdgcn_fence(__ATOMIC_RELEASE, "agent");
;             asm volatile("s_waitcnt vmcnt(0)" ::: "memory");
;             const unsigned og = xb_add(&bar[XB_TOP], 1u);
;             const unsigned tg = og / nx;
;             if (og + 1u == (tg + 1u) * nx) xb_add(&bar[XB_TOPGEN], 1u);
;             else XB_SPIN(xb_ld(&bar[XB_TOPGEN]) == tg, bar);
;             __builtin_amdgcn_fence(__ATOMIC_ACQUIRE, "agent");
;             xb_add(&bar[XB_XGEN(b.x)], 1u);
;             asm volatile("s_waitcnt vmcnt(0)" ::: "memory");
.LBB0_3899:
	s_or_b64 exec, exec, s[38:39]
	s_mov_b64 s[38:39], exec
	v_mbcnt_lo_u32_b32 v0, s38, 0
	v_mbcnt_hi_u32_b32 v0, s39, v0
	v_cmp_eq_u32_e32 vcc, 0, v0
	s_waitcnt vmcnt(0)
	buffer_inv sc1
	s_and_saveexec_b64 s[40:41], vcc
	s_cbranch_execz .LBB0_3901
	s_bcnt1_i32_b64 s6, s[38:39]
	v_mov_b32_e32 v0, s6
	v_readlane_b32 s6, v252, 53
	v_readlane_b32 s7, v252, 54
	s_nop 4
.LBB0_3901:
	s_or_b64 exec, exec, s[40:41]
	s_waitcnt vmcnt(0)

; __device__ __forceinline__ unsigned xb_ld(unsigned* p)              { return __hip_atomic_load(p, __ATOMIC_RELAXED, __HIP_MEMORY_SCOPE_AGENT); }
; __device__ __forceinline__ unsigned xb_add(unsigned* p, unsigned v) { return __hip_atomic_fetch_add(p, v, __ATOMIC_RELAXED, __HIP_MEMORY_SCOPE_AGENT); }
; #define XB_SPIN(cond, bar) do { unsigned _sp = 0; while (cond) { __builtin_amdgcn_s_sleep(1); \
;     if ((++_sp & 255u) == 0u) { if (xb_ld(&(bar)[XB_TMO])) break; if (_sp > XB_SPIN_CAP) { atomicAdd(&(bar)[XB_TMO], 1u); break; } } } } while (0)
; __device__ __forceinline__ void xcd_barrier(const XcdBarrier& b) {
;     ...
;         if (old + 1u == (gen + 1u) * nloc) {
;             __builtin_amdgcn_fence(__ATOMIC_RELEASE, "agent");
;             asm volatile("s_waitcnt vmcnt(0)" ::: "memory");
;             const unsigned og = xb_add(&bar[XB_TOP], 1u);
;             const unsigned tg = og / nx;
;             if (og + 1u == (tg + 1u) * nx) xb_add(&bar[XB_TOPGEN], 1u);
;             else XB_SPIN(xb_ld(&bar[XB_TOPGEN]) == tg, bar);
;             __builtin_amdgcn_fence(__ATOMIC_ACQUIRE, "agent");
;             xb_add(&bar[XB_XGEN(b.x)], 1u);
;             asm volatile("s_waitcnt vmcnt(0)" ::: "memory");
.LBB0_3994:
	s_bcnt1_i32_b64 s2, s[2:3]
	v_mov_b32_e32 v0, s2
	v_readlane_b32 s2, v252, 53
	v_readlane_b32 s3, v252, 54
	s_nop 4
	s_getpc_b64 s[98:99]
